# barrier GEMM2->final norm waits only for the 32 workgroups of its XCD group (final rows remapped to the group that produced them; hardware XCC id checked at start with grid-wide fallback); non-last ar
# speedup vs baseline: 1.0271x; 1.0006x over previous
.LBB0_2:
	s_or_b64 exec, exec, s[4:5]
	s_load_dwordx16 s[4:19], s[0:1], 0x0
	s_load_dwordx16 s[72:87], s[0:1], 0x80
	s_waitcnt lgkmcnt(0)
	s_barrier
	s_getreg_b32 s33, hwreg(HW_REG_XCC_ID, 0, 4)
	s_and_b32 s36, s33, 15
	s_and_saveexec_b64 s[22:23], s[92:93]
	s_cbranch_execz .LBB0_5
	s_mov_b64 s[24:25], exec
	v_mbcnt_lo_u32_b32 v1, s24, 0
	v_mbcnt_hi_u32_b32 v1, s25, v1
	v_cmp_eq_u32_e32 vcc, 0, v1
	s_and_b64 s[26:27], exec, vcc
	s_mov_b64 exec, s[26:27]
	s_cbranch_execz .LBB0_5
	s_lshl_b32 s26, s36, 8
	s_bcnt1_i32_b64 s24, s[24:25]
	v_mov_b32_e32 v1, s26
	v_mov_b32_e32 v2, s24
	global_atomic_add v1, v2, s[88:89] offset:1024
	s_and_b32 s26, s2, 7
	s_cmp_lg_u32 s26, s36
	s_cselect_b32 s26, 1, 0
	s_cmp_lg_u32 s90, 0x100
	s_cselect_b32 s24, 1, 0
	s_or_b32 s26, s26, s24
	s_cmp_eq_u32 s26, 0
	s_cbranch_scc1 .Lxg_ok
	v_mov_b32_e32 v1, 0x4c00
	v_mov_b32_e32 v2, 1
	global_atomic_add v1, v2, s[88:89]
.Lxg_ok:
.LBB0_5:
	s_or_b64 exec, exec, s[22:23]
	s_load_dwordx16 s[52:67], s[0:1], 0x40
	v_and_b32_e32 v174, 63, v141
	s_cmpk_gt_i32 s2, 0xdbf
	v_lshrrev_b32_e32 v175, 6, v141
	v_mov_b32_e32 v35, 0
	v_lshlrev_b32_e32 v142, 4, v174
	v_lshlrev_b32_e32 v144, 2, v174
	s_cbranch_scc1 .LBB0_42
	v_mul_u32_u24_e32 v2, 0x104, v175
	v_lshlrev_b32_e32 v1, 9, v141
	v_mov_b32_e32 v143, v35
	v_lshlrev_b32_e32 v34, 3, v174
	v_add3_u32 v46, v2, v144, 0
	v_mul_u32_u24_e32 v2, 0x104, v174
	v_lshlrev_b32_e32 v3, 2, v175
	v_and_b32_e32 v1, 0x7e00, v1
	v_lshlrev_b32_e32 v43, 1, v175
	v_lshl_add_u64 v[36:37], s[4:5], 0, v[142:143]
	v_lshl_add_u64 v[38:39], s[6:7], 0, v[142:143]
	v_lshl_add_u64 v[40:41], s[72:73], 0, v[34:35]
	s_mov_b32 s7, 0
	v_lshl_or_b32 v47, v175, 10, v174
	v_add3_u32 v48, v2, v3, 0
	s_mov_b32 s22, 0x3a800000
	s_mov_b32 s23, 0x800000
	v_mov_b32_e32 v42, 0x358637bd
	global_load_dwordx4 v[84:87], v[38:39], off
	global_load_dwordx4 v[88:91], v[38:39], off offset:1024
	global_load_dwordx4 v[92:95], v[38:39], off offset:2048
	global_load_dwordx4 v[96:99], v[38:39], off offset:3072
	s_mov_b32 s30, s2
	s_branch .LBB0_8

.LBB0_72:
	s_or_b64 exec, exec, s[36:37]
	v_cvt_f32_u32_e32 v4, v2
	s_waitcnt vmcnt(0)
	v_readfirstlane_b32 s22, v3
	v_sub_u32_e32 v3, 0, v2
	v_rcp_iflag_f32_e32 v4, v4
	v_add_u32_e32 v5, s22, v1
	v_mul_f32_e32 v4, 0x4f7ffffe, v4
	v_cvt_u32_f32_e32 v4, v4
	v_mul_lo_u32 v1, v3, v4
	v_mul_hi_u32 v1, v4, v1
	v_add_u32_e32 v1, v4, v1
	v_mul_hi_u32 v1, v5, v1
	v_mul_lo_u32 v3, v1, v2
	v_sub_u32_e32 v3, v5, v3
	v_add_u32_e32 v4, 1, v1
	v_cmp_ge_u32_e32 vcc, v3, v2
	s_nop 1
	v_cndmask_b32_e32 v1, v1, v4, vcc
	v_sub_u32_e32 v4, v3, v2
	v_cndmask_b32_e32 v3, v3, v4, vcc
	v_add_u32_e32 v4, 1, v1
	v_cmp_ge_u32_e32 vcc, v3, v2
	v_add_u32_e32 v3, 1, v5
	s_nop 0
	v_cndmask_b32_e32 v1, v1, v4, vcc
	v_mul_lo_u32 v4, v2, v1
	v_add_u32_e32 v2, v4, v2
	v_cmp_ne_u32_e32 vcc, v3, v2
	s_and_saveexec_b64 s[22:23], vcc
	s_xor_b64 s[36:37], exec, s[22:23]
	s_cbranch_execz .LBB0_86
	s_waitcnt lgkmcnt(0)
	v_mov_b32_e32 v0, 0
	global_load_dword v2, v0, s[14:15] sc1
	s_waitcnt vmcnt(0)
	v_cmp_eq_u32_e32 vcc, v2, v1
	s_and_saveexec_b64 s[38:39], vcc
	s_cbranch_execz .LBB0_85
	s_mov_b32 s22, 1
	s_mov_b64 s[40:41], 0
	s_branch .LBB0_76

.LBB0_80:
	global_load_dword v2, v0, s[14:15] sc1
	s_add_i32 s22, s22, 1
	s_mov_b64 s[46:47], -1
	s_waitcnt vmcnt(0)
	v_cmp_ne_u32_e32 vcc, v2, v1
	s_orn2_b64 s[44:45], vcc, exec
	s_branch .LBB0_75

.LBB0_1082:
	s_or_b64 exec, exec, s[12:13]
	v_cvt_f32_u32_e32 v4, v2
	s_waitcnt vmcnt(0)
	v_readfirstlane_b32 s12, v3
	v_sub_u32_e32 v3, 0, v2
	v_rcp_iflag_f32_e32 v4, v4
	v_add_u32_e32 v5, s12, v1
	v_mul_f32_e32 v4, 0x4f7ffffe, v4
	v_cvt_u32_f32_e32 v4, v4
	v_mul_lo_u32 v1, v3, v4
	v_mul_hi_u32 v1, v4, v1
	v_add_u32_e32 v1, v4, v1
	v_mul_hi_u32 v1, v5, v1
	v_mul_lo_u32 v3, v1, v2
	v_sub_u32_e32 v3, v5, v3
	v_add_u32_e32 v4, 1, v1
	v_cmp_ge_u32_e32 vcc, v3, v2
	s_nop 1
	v_cndmask_b32_e32 v1, v1, v4, vcc
	v_sub_u32_e32 v4, v3, v2
	v_cndmask_b32_e32 v3, v3, v4, vcc
	v_add_u32_e32 v4, 1, v1
	v_cmp_ge_u32_e32 vcc, v3, v2
	v_add_u32_e32 v3, 1, v5
	s_nop 0
	v_cndmask_b32_e32 v1, v1, v4, vcc
	v_mul_lo_u32 v4, v2, v1
	v_add_u32_e32 v2, v4, v2
	v_cmp_ne_u32_e32 vcc, v3, v2
	s_and_saveexec_b64 s[12:13], vcc
	s_xor_b64 s[12:13], exec, s[12:13]
	s_cbranch_execz .LBB0_1096
	s_waitcnt lgkmcnt(0)
	v_mov_b32_e32 v0, 0
	global_load_dword v2, v0, s[14:15] sc1
	s_waitcnt vmcnt(0)
	v_cmp_eq_u32_e32 vcc, v2, v1
	s_and_saveexec_b64 s[16:17], vcc
	s_cbranch_execz .LBB0_1095
	s_mov_b32 s22, 1
	s_mov_b64 s[18:19], 0
	s_branch .LBB0_1086

.LBB0_1090:
	global_load_dword v2, v0, s[14:15] sc1
	s_add_i32 s22, s22, 1
	s_mov_b64 s[40:41], -1
	s_waitcnt vmcnt(0)
	v_cmp_ne_u32_e32 vcc, v2, v1
	s_orn2_b64 s[38:39], vcc, exec
	s_branch .LBB0_1085

.LBB0_1187:
	s_or_b64 exec, exec, s[12:13]
	v_cvt_f32_u32_e32 v4, v2
	s_waitcnt vmcnt(0)
	v_readfirstlane_b32 s12, v3
	v_sub_u32_e32 v3, 0, v2
	v_rcp_iflag_f32_e32 v4, v4
	v_add_u32_e32 v5, s12, v1
	v_mul_f32_e32 v4, 0x4f7ffffe, v4
	v_cvt_u32_f32_e32 v4, v4
	v_mul_lo_u32 v1, v3, v4
	v_mul_hi_u32 v1, v4, v1
	v_add_u32_e32 v1, v4, v1
	v_mul_hi_u32 v1, v5, v1
	v_mul_lo_u32 v3, v1, v2
	v_sub_u32_e32 v3, v5, v3
	v_add_u32_e32 v4, 1, v1
	v_cmp_ge_u32_e32 vcc, v3, v2
	s_nop 1
	v_cndmask_b32_e32 v1, v1, v4, vcc
	v_sub_u32_e32 v4, v3, v2
	v_cndmask_b32_e32 v3, v3, v4, vcc
	v_add_u32_e32 v4, 1, v1
	v_cmp_ge_u32_e32 vcc, v3, v2
	v_add_u32_e32 v3, 1, v5
	s_nop 0
	v_cndmask_b32_e32 v1, v1, v4, vcc
	v_mul_lo_u32 v4, v2, v1
	v_add_u32_e32 v2, v4, v2
	v_cmp_ne_u32_e32 vcc, v3, v2
	s_and_saveexec_b64 s[12:13], vcc
	s_xor_b64 s[12:13], exec, s[12:13]
	s_cbranch_execz .LBB0_1201
	s_waitcnt lgkmcnt(0)
	v_mov_b32_e32 v0, 0
	global_load_dword v2, v0, s[14:15] sc1
	s_waitcnt vmcnt(0)
	v_cmp_eq_u32_e32 vcc, v2, v1
	s_and_saveexec_b64 s[16:17], vcc
	s_cbranch_execz .LBB0_1200
	s_mov_b32 s23, 1
	s_mov_b64 s[18:19], 0
	s_branch .LBB0_1191

.LBB0_1195:
	global_load_dword v2, v0, s[14:15] sc1
	s_add_i32 s23, s23, 1
	s_mov_b64 s[40:41], -1
	s_waitcnt vmcnt(0)
	v_cmp_ne_u32_e32 vcc, v2, v1
	s_orn2_b64 s[38:39], vcc, exec
	s_branch .LBB0_1190

.LBB0_1242:
	s_or_b64 exec, exec, s[16:17]
	v_cvt_f32_u32_e32 v4, v2
	s_waitcnt vmcnt(0)
	v_readfirstlane_b32 s16, v3
	v_sub_u32_e32 v3, 0, v2
	v_rcp_iflag_f32_e32 v4, v4
	v_add_u32_e32 v5, s16, v1
	v_mul_f32_e32 v4, 0x4f7ffffe, v4
	v_cvt_u32_f32_e32 v4, v4
	v_mul_lo_u32 v1, v3, v4
	v_mul_hi_u32 v1, v4, v1
	v_add_u32_e32 v1, v4, v1
	v_mul_hi_u32 v1, v5, v1
	v_mul_lo_u32 v3, v1, v2
	v_sub_u32_e32 v3, v5, v3
	v_add_u32_e32 v4, 1, v1
	v_cmp_ge_u32_e32 vcc, v3, v2
	s_nop 1
	v_cndmask_b32_e32 v1, v1, v4, vcc
	v_sub_u32_e32 v4, v3, v2
	v_cndmask_b32_e32 v3, v3, v4, vcc
	v_add_u32_e32 v4, 1, v1
	v_cmp_ge_u32_e32 vcc, v3, v2
	v_add_u32_e32 v3, 1, v5
	s_nop 0
	v_cndmask_b32_e32 v1, v1, v4, vcc
	v_mul_lo_u32 v4, v2, v1
	v_add_u32_e32 v2, v4, v2
	v_cmp_ne_u32_e32 vcc, v3, v2
	s_and_saveexec_b64 s[16:17], vcc
	s_xor_b64 s[16:17], exec, s[16:17]
	s_cbranch_execz .LBB0_1256
	s_waitcnt lgkmcnt(0)
	v_mov_b32_e32 v0, 0
	global_load_dword v2, v0, s[14:15] sc1
	s_waitcnt vmcnt(0)
	v_cmp_eq_u32_e32 vcc, v2, v1
	s_and_saveexec_b64 s[18:19], vcc
	s_cbranch_execz .LBB0_1255
	s_mov_b32 s22, 1
	s_mov_b64 s[36:37], 0
	s_branch .LBB0_1246

.LBB0_1250:
	global_load_dword v2, v0, s[14:15] sc1
	s_add_i32 s22, s22, 1
	s_mov_b64 s[42:43], -1
	s_waitcnt vmcnt(0)
	v_cmp_ne_u32_e32 vcc, v2, v1
	s_orn2_b64 s[40:41], vcc, exec
	s_branch .LBB0_1245

.LBB0_1302:
	s_waitcnt vmcnt(0)
	s_barrier
	s_and_saveexec_b64 s[4:5], s[92:93]
	s_cbranch_execz .LBB0_1354
	s_add_u32 s12, s88, 0x4000
	s_addc_u32 s13, s89, 0
	v_mov_b32_e32 v0, 0
	global_load_dword v2, v0, s[12:13] offset:3072 sc1
	s_and_b32 s0, s2, 7
	s_lshl_b32 s0, s0, 7
	v_mov_b32_e32 v3, s0
	v_mov_b32_e32 v4, 1
	s_waitcnt vmcnt(0)
	v_readfirstlane_b32 s32, v2
	s_nop 3
	s_cmp_lg_u32 s32, 0
	s_cbranch_scc1 .Lgb6_slow
	global_atomic_add v3, v4, s[12:13] offset:2048
	s_mov_b32 s0, 0
.Lgb6_spin:
	global_load_dword v2, v3, s[12:13] offset:2048 sc1
	s_waitcnt vmcnt(0)
	v_cmp_le_u32_e32 vcc, 32, v2
	s_cbranch_vccnz .Lgb6_done
	s_sleep 1
	s_add_i32 s0, s0, 1
	s_cmp_lt_u32 s0, 0x100000
	s_cbranch_scc1 .Lgb6_spin
.Lgb6_done:
	buffer_inv sc1
	s_waitcnt vmcnt(0)
	s_branch .LBB0_1354
.Lgb6_slow:
	s_add_i32 s12, 0, 0x25e00
	v_mov_b32_e32 v0, s12
	s_waitcnt vmcnt(0) expcnt(0) lgkmcnt(0)
	ds_read_b32 v2, v0
	s_add_i32 s12, 0, 0x25e04
	v_mov_b32_e32 v0, s12
	ds_read_b32 v0, v0
	s_waitcnt lgkmcnt(1)
	v_cmp_ne_u32_e32 vcc, 0, v2
	s_cbranch_vccnz .LBB0_1318
	s_mov_b32 s22, 1
	v_mov_b32_e32 v16, 0
	s_branch .LBB0_1306

.LBB0_1320:
	s_or_b64 exec, exec, s[0:1]
	v_cvt_f32_u32_e32 v4, v2
	s_waitcnt vmcnt(0)
	v_readfirstlane_b32 s0, v3
	v_sub_u32_e32 v3, 0, v2
	v_rcp_iflag_f32_e32 v4, v4
	v_add_u32_e32 v5, s0, v1
	v_mul_f32_e32 v4, 0x4f7ffffe, v4
	v_cvt_u32_f32_e32 v4, v4
	v_mul_lo_u32 v1, v3, v4
	v_mul_hi_u32 v1, v4, v1
	v_add_u32_e32 v1, v4, v1
	v_mul_hi_u32 v1, v5, v1
	v_mul_lo_u32 v3, v1, v2
	v_sub_u32_e32 v3, v5, v3
	v_add_u32_e32 v4, 1, v1
	v_cmp_ge_u32_e32 vcc, v3, v2
	s_nop 1
	v_cndmask_b32_e32 v1, v1, v4, vcc
	v_sub_u32_e32 v4, v3, v2
	v_cndmask_b32_e32 v3, v3, v4, vcc
	v_add_u32_e32 v4, 1, v1
	v_cmp_ge_u32_e32 vcc, v3, v2
	v_add_u32_e32 v3, 1, v5
	s_nop 0
	v_cndmask_b32_e32 v1, v1, v4, vcc
	v_mul_lo_u32 v4, v2, v1
	v_add_u32_e32 v2, v4, v2
	v_cmp_ne_u32_e32 vcc, v3, v2
	s_and_saveexec_b64 s[0:1], vcc
	s_xor_b64 s[0:1], exec, s[0:1]
	s_cbranch_execz .LBB0_1334
	s_waitcnt lgkmcnt(0)
	v_mov_b32_e32 v0, 0
	global_load_dword v2, v0, s[14:15] sc1
	s_waitcnt vmcnt(0)
	v_cmp_eq_u32_e32 vcc, v2, v1
	s_and_saveexec_b64 s[12:13], vcc
	s_cbranch_execz .LBB0_1333
	s_mov_b32 s3, 1
	s_mov_b64 s[16:17], 0
	s_branch .LBB0_1324

.LBB0_1328:
	global_load_dword v2, v0, s[14:15] sc1
	s_add_i32 s3, s3, 1
	s_mov_b64 s[22:23], -1
	s_waitcnt vmcnt(0)
	v_cmp_ne_u32_e32 vcc, v2, v1
	s_orn2_b64 s[20:21], vcc, exec
	s_branch .LBB0_1323

.LBB0_1354:
	s_or_b64 exec, exec, s[4:5]
	s_and_b64 vcc, exec, s[10:11]
	s_waitcnt lgkmcnt(0)
	s_barrier
	s_cbranch_vccz .LBB0_1357
	v_and_b32_e32 v2, 0x1f8, v154
	s_waitcnt vmcnt(13)
	v_mov_b32_e32 v5, 0
	v_and_b32_e32 v6, 30, v162
	v_lshlrev_b32_e32 v4, 2, v2
	v_lshlrev_b32_e32 v2, 1, v2
	v_mov_b32_e32 v3, v5
	v_lshl_add_u64 v[0:1], s[52:53], 0, v[4:5]
	v_lshl_add_u64 v[2:3], s[86:87], 0, v[2:3]
	v_lshl_add_u64 v[4:5], s[54:55], 0, v[4:5]
	s_mov_b32 s13, s90
	s_movk_i32 s12, 0x7ff
	s_cmp_lg_u32 s90, 0x100
	s_cbranch_scc1 .Lfn_plain
	s_and_b32 s0, s2, 7
	s_lshr_b32 s1, s2, 3
	s_lshl_b32 s0, s0, 8
	s_add_i32 s2, s0, s1
	s_add_i32 s12, s0, 0xff
	s_mov_b32 s13, 32
.Lfn_plain:
	v_lshl_add_u32 v6, s2, 4, v6
	s_lshl_b32 s1, s13, 4
	s_mov_b32 s0, 0x3a800000
	v_mov_b32_e32 v8, 0x358637bd
	s_mov_b32 s3, 0x800000
.LBB0_1356:
	v_ashrrev_i32_e32 v7, 31, v6
	v_lshlrev_b64 v[10:11], 11, v[6:7]
	v_lshl_add_u64 v[14:15], v[2:3], 0, v[10:11]
	global_load_dwordx4 v[10:13], v[14:15], off offset:1024
	global_load_dwordx4 v[16:19], v[14:15], off offset:3072
	global_load_dwordx4 v[20:23], v[14:15], off
	global_load_dwordx4 v[24:27], v[14:15], off offset:2048
	global_load_dwordx4 v[28:31], v[0:1], off
	global_load_dwordx4 v[32:35], v[0:1], off offset:16
	s_add_i32 s2, s2, s13
	s_cmp_gt_i32 s2, s12
	s_waitcnt vmcnt(5)
	v_lshlrev_b32_e32 v37, 16, v11
	v_lshlrev_b32_e32 v36, 16, v10
	v_and_b32_e32 v39, 0xffff0000, v11
	v_and_b32_e32 v38, 0xffff0000, v10
	v_lshlrev_b32_e32 v41, 16, v13
	v_lshlrev_b32_e32 v40, 16, v12
	v_and_b32_e32 v43, 0xffff0000, v13
	v_and_b32_e32 v42, 0xffff0000, v12
	s_waitcnt vmcnt(4)
	v_lshlrev_b32_e32 v13, 16, v17
	v_lshlrev_b32_e32 v12, 16, v16
	v_and_b32_e32 v11, 0xffff0000, v17
	v_and_b32_e32 v10, 0xffff0000, v16
	v_lshlrev_b32_e32 v17, 16, v19
	v_lshlrev_b32_e32 v16, 16, v18
	v_and_b32_e32 v15, 0xffff0000, v19
	v_and_b32_e32 v14, 0xffff0000, v18
	s_waitcnt vmcnt(3)
	v_lshlrev_b32_e32 v18, 16, v22
	v_and_b32_e32 v19, 0xffff0000, v22
	v_lshlrev_b32_e32 v22, 16, v23
	v_and_b32_e32 v23, 0xffff0000, v23
	v_lshlrev_b32_e32 v44, 16, v20
	v_and_b32_e32 v45, 0xffff0000, v20
	v_lshlrev_b32_e32 v46, 16, v21
	v_and_b32_e32 v47, 0xffff0000, v21
	s_waitcnt vmcnt(2)
	v_lshlrev_b32_e32 v48, 16, v26
	v_and_b32_e32 v49, 0xffff0000, v26
	v_lshlrev_b32_e32 v26, 16, v27
	v_and_b32_e32 v27, 0xffff0000, v27
	v_lshlrev_b32_e32 v50, 16, v24
	v_and_b32_e32 v51, 0xffff0000, v24
	v_lshlrev_b32_e32 v52, 16, v25
	v_and_b32_e32 v53, 0xffff0000, v25
	v_mov_b32_e32 v60, v23
	v_mov_b32_e32 v61, v19
	v_pk_mul_f32 v[62:63], v[44:45], v[44:45]
	v_pk_mul_f32 v[64:65], v[46:47], v[46:47]
	v_mov_b32_e32 v58, v22
	v_mov_b32_e32 v59, v18
	v_mov_b32_e32 v68, v27
	v_mov_b32_e32 v69, v49
	v_pk_mul_f32 v[70:71], v[50:51], v[50:51]
	v_pk_mul_f32 v[72:73], v[52:53], v[52:53]
	v_pk_mul_f32 v[60:61], v[60:61], v[60:61]
	v_add_f32_e32 v9, v64, v65
	v_add_f32_e32 v64, v62, v63
	v_mov_b32_e32 v66, v26
	v_mov_b32_e32 v67, v48
	v_pk_mul_f32 v[62:63], v[68:69], v[68:69]
	v_add_f32_e32 v65, v72, v73
	v_add_f32_e32 v68, v70, v71
	v_pk_fma_f32 v[58:59], v[58:59], v[58:59], v[60:61]
	v_add_f32_e32 v9, v64, v9
	v_pk_mul_f32 v[20:21], v[38:39], v[38:39]
	v_pk_fma_f32 v[60:61], v[66:67], v[66:67], v[62:63]
	v_add_f32_e32 v62, v68, v65
	v_add_f32_e32 v9, v59, v9
	v_pk_mul_f32 v[54:55], v[10:11], v[10:11]
	v_pk_fma_f32 v[20:21], v[36:37], v[36:37], v[20:21]
	v_add_f32_e32 v59, v61, v62
	v_add_f32_e32 v9, v58, v9
	v_pk_mul_f32 v[24:25], v[42:43], v[42:43]
	v_pk_fma_f32 v[54:55], v[12:13], v[12:13], v[54:55]
	v_add_f32_e32 v58, v60, v59
	v_add_f32_e32 v9, v20, v9
	v_pk_mul_f32 v[56:57], v[14:15], v[14:15]
	v_pk_fma_f32 v[24:25], v[40:41], v[40:41], v[24:25]
	v_add_f32_e32 v20, v54, v58
	v_add_f32_e32 v9, v21, v9
	v_pk_fma_f32 v[56:57], v[16:17], v[16:17], v[56:57]
	v_add_f32_e32 v20, v55, v20
	v_add_f32_e32 v9, v24, v9
	v_add_f32_e32 v20, v56, v20
	v_add_f32_e32 v9, v25, v9
	v_add_f32_e32 v20, v57, v20
	v_mov_b32_e32 v21, v9
	v_mov_b32_e32 v24, v20
	s_nop 0
	v_mov_b32_dpp v21, v21 quad_perm:[1,0,3,2] row_mask:0xf bank_mask:0xf
	v_mov_b32_dpp v24, v24 quad_perm:[1,0,3,2] row_mask:0xf bank_mask:0xf
	v_add_f32_e32 v9, v9, v21
	v_add_f32_e32 v20, v20, v24
	v_mov_b32_e32 v21, v9
	v_mov_b32_e32 v24, v20
	s_nop 0
	v_mov_b32_dpp v21, v21 quad_perm:[2,3,0,1] row_mask:0xf bank_mask:0xf
	v_mov_b32_dpp v24, v24 quad_perm:[2,3,0,1] row_mask:0xf bank_mask:0xf
	v_add_f32_e32 v9, v9, v21
	v_add_f32_e32 v24, v20, v24
	v_mov_b32_e32 v20, v9
	s_nop 1
	v_mov_b32_dpp v20, v20 row_half_mirror row_mask:0xf bank_mask:0xf
	v_add_f32_e32 v9, v9, v20
	v_mov_b32_e32 v20, v9
	s_nop 1
	v_mov_b32_dpp v20, v20 row_mirror row_mask:0xf bank_mask:0xf
	v_add_f32_e32 v9, v9, v20
	s_nop 0
	v_readlane_b32 s4, v9, 0
	v_readlane_b32 s6, v9, 16
	v_readlane_b32 s5, v9, 32
	v_readlane_b32 s7, v9, 48
	v_mov_b32_e32 v9, v24
	v_mov_b32_e32 v20, s6
	v_mov_b32_e32 v21, s7
	v_mov_b32_dpp v9, v9 row_half_mirror row_mask:0xf bank_mask:0xf
	v_add_f32_e32 v9, v24, v9
	v_mov_b32_e32 v24, v9
	v_pk_add_f32 v[20:21], s[4:5], v[20:21]
	s_nop 0
	v_mov_b32_dpp v24, v24 row_mirror row_mask:0xf bank_mask:0xf
	v_add_f32_e32 v9, v9, v24
	v_mov_b32_e32 v55, v20
	v_readlane_b32 s6, v9, 16
	v_readlane_b32 s7, v9, 48
	v_readlane_b32 s4, v9, 0
	v_readlane_b32 s5, v9, 32
	v_mov_b32_e32 v24, s6
	v_mov_b32_e32 v25, s7
	v_pk_add_f32 v[24:25], s[4:5], v[24:25]
	s_nop 0
	v_mov_b32_e32 v54, v24
	v_mov_b32_e32 v20, v25
	v_pk_add_f32 v[20:21], v[54:55], v[20:21]
	s_nop 0
	v_pk_fma_f32 v[54:55], v[20:21], s[0:1], v[8:9] op_sel_hi:[1,0,0]
	v_lshlrev_b64 v[20:21], 12, v[6:7]
	v_mul_f32_e32 v9, 0x4b800000, v55
	v_cmp_gt_f32_e32 vcc, s3, v55
	v_lshl_add_u64 v[56:57], v[4:5], 0, v[20:21]
	s_nop 0
	v_cndmask_b32_e32 v9, v55, v9, vcc
	v_rsq_f32_e32 v9, v9
	s_nop 0
	v_mul_f32_e32 v7, 0x45800000, v9
	v_cndmask_b32_e32 v58, v9, v7, vcc
	v_pk_mul_f32 v[20:21], v[58:59], v[22:23] op_sel_hi:[0,1]
	v_pk_mul_f32 v[22:23], v[58:59], v[44:45] op_sel_hi:[0,1]
	v_pk_mul_f32 v[24:25], v[58:59], v[46:47] op_sel_hi:[0,1]
	v_pk_mul_f32 v[18:19], v[58:59], v[18:19] op_sel_hi:[0,1]
	s_waitcnt vmcnt(1)
	v_pk_mul_f32 v[24:25], v[30:31], v[24:25]
	v_pk_mul_f32 v[22:23], v[28:29], v[22:23]
	s_waitcnt vmcnt(0)
	v_pk_mul_f32 v[18:19], v[32:33], v[18:19]
	v_pk_mul_f32 v[20:21], v[34:35], v[20:21]
	global_store_dwordx4 v[56:57], v[22:25], off nt
	global_store_dwordx4 v[56:57], v[18:21], off offset:16 nt
	global_load_dwordx4 v[18:21], v[0:1], off offset:2048
	s_nop 0
	global_load_dwordx4 v[22:25], v[0:1], off offset:2064
	v_mov_b32_e32 v28, v36
	v_mov_b32_e32 v29, v38
	v_mov_b32_e32 v38, v37
	v_mov_b32_e32 v30, v40
	v_mov_b32_e32 v31, v42
	v_mov_b32_e32 v42, v41
	v_pk_mul_f32 v[28:29], v[58:59], v[28:29] op_sel_hi:[0,1]
	v_pk_mul_f32 v[32:33], v[58:59], v[38:39] op_sel_hi:[0,1]
	v_pk_mul_f32 v[30:31], v[58:59], v[30:31] op_sel_hi:[0,1]
	v_pk_mul_f32 v[34:35], v[58:59], v[42:43] op_sel_hi:[0,1]
	v_mul_f32_e32 v7, 0x4b800000, v54
	v_cmp_gt_f32_e32 vcc, s3, v54
	s_waitcnt vmcnt(1)
	v_pk_mul_f32 v[18:19], v[28:29], v[18:19]
	v_pk_mul_f32 v[20:21], v[32:33], v[20:21]
	s_waitcnt vmcnt(0)
	v_pk_mul_f32 v[22:23], v[30:31], v[22:23]
	v_pk_mul_f32 v[24:25], v[34:35], v[24:25]
	global_store_dwordx4 v[56:57], v[18:21], off offset:2048 nt
	global_store_dwordx4 v[56:57], v[22:25], off offset:2064 nt
	global_load_dwordx4 v[18:21], v[0:1], off offset:16
	s_nop 0
	global_load_dwordx4 v[22:25], v[0:1], off
	v_cndmask_b32_e32 v7, v54, v7, vcc
	v_rsq_f32_e32 v7, v7
	v_add_u32_e32 v28, 1, v6
	v_ashrrev_i32_e32 v29, 31, v28
	v_lshlrev_b64 v[28:29], 12, v[28:29]
	v_mul_f32_e32 v9, 0x45800000, v7
	v_cndmask_b32_e32 v30, v7, v9, vcc
	v_pk_mul_f32 v[34:35], v[30:31], v[52:53] op_sel_hi:[0,1]
	v_pk_mul_f32 v[36:37], v[30:31], v[50:51] op_sel_hi:[0,1]
	v_lshl_add_u64 v[28:29], v[4:5], 0, v[28:29]
	v_pk_mul_f32 v[32:33], v[30:31], v[48:49] op_sel_hi:[0,1]
	v_pk_mul_f32 v[26:27], v[30:31], v[26:27] op_sel_hi:[0,1]
	v_add_u32_e32 v6, s1, v6
	s_waitcnt vmcnt(1)
	v_pk_mul_f32 v[18:19], v[18:19], v[32:33]
	s_waitcnt vmcnt(0)
	v_pk_mul_f32 v[22:23], v[22:23], v[36:37]
	v_pk_mul_f32 v[24:25], v[24:25], v[34:35]
	v_pk_mul_f32 v[20:21], v[20:21], v[26:27]
	global_store_dwordx4 v[28:29], v[22:25], off nt
	global_store_dwordx4 v[28:29], v[18:21], off offset:16 nt
	global_load_dwordx4 v[18:21], v[0:1], off offset:2048
	s_nop 0
	global_load_dwordx4 v[22:25], v[0:1], off offset:2064
	v_mov_b32_e32 v26, v12
	v_mov_b32_e32 v27, v10
	v_mov_b32_e32 v10, v13
	v_mov_b32_e32 v32, v16
	v_mov_b32_e32 v33, v14
	v_mov_b32_e32 v14, v17
	v_pk_mul_f32 v[12:13], v[30:31], v[26:27] op_sel_hi:[0,1]
	v_pk_mul_f32 v[26:27], v[30:31], v[10:11] op_sel_hi:[0,1]
	v_pk_mul_f32 v[16:17], v[30:31], v[32:33] op_sel_hi:[0,1]
	v_pk_mul_f32 v[30:31], v[30:31], v[14:15] op_sel_hi:[0,1]
	s_waitcnt vmcnt(1)
	v_pk_mul_f32 v[10:11], v[12:13], v[18:19]
	v_pk_mul_f32 v[12:13], v[26:27], v[20:21]
	s_waitcnt vmcnt(0)
	v_pk_mul_f32 v[14:15], v[16:17], v[22:23]
	v_pk_mul_f32 v[16:17], v[30:31], v[24:25]
	global_store_dwordx4 v[28:29], v[10:13], off offset:2048 nt
	global_store_dwordx4 v[28:29], v[14:17], off offset:2064 nt
	s_cbranch_scc0 .LBB0_1356
